# P2 K/V and Q register prefetch two units ahead (second landing sets, parity-selected), bias table reloaded only on head change; on top of the fused P9
# baseline (speedup 1.0000x reference)
; #define LAS __attribute__((address_space(3)))
; __device__ __forceinline__ void attn_issue(AttnRegs& R, const AttnUnit& u, int blk, bool with_q, const bf16* qkv, const float* bias2) {
;     const int tid = threadIdx.x, lane = tid & 63, w = tid >> 6;
;     const int L = 4096 >> (2 * u.g), gh = u.g * 8 + u.h;
;     const int ch = tid & 15, r0 = tid >> 4;
;     if (with_q) R.tabv = bias2[gh * 192 + (tid < 192 ? tid : 0)];
;     const size_t rb = (size_t)(u.r * L + blk * 128 + r0) * 128 + ch * 8;
;     const bf16* kp = attn_plane(qkv, 1, u) + rb; const bf16* vp = attn_plane(qkv, 2, u) + rb;
; #pragma unroll
;     for (int j = 0; j < 4; ++j) { R.kr[j] = *(const v4u*)(kp + (size_t)j * 32 * 128); R.vr[j] = *(const v4u*)(vp + (size_t)j * 32 * 128); }
;     if (with_q) {
;         const int qi = 16 * w + (lane & 15), kg = lane >> 4;
;         const bf16* qp = attn_plane(qkv, 0, u) + (size_t)(u.r * L + u.n * 128 + qi) * 128 + 8 * kg;
; #pragma unroll
;         for (int s = 0; s < 4; ++s) R.qf[s] = *(const bf16x8*)(qp + 32 * s);
;     }
; __global__ void __launch_bounds__(NTHREADS, 2) fwd_megakernel(Args args) {
;     ...
;         const int per = (NUNITS + G - 1) / G;
;         const int u0 = vcu * per, u1 = (u0 + per < NUNITS) ? u0 + per : NUNITS;
;         { const v4u z = {0u, 0u, 0u, 0u}; for (int i = threadIdx.x; i < 8192; i += NTHREADS) *(LAS v4u*)(lds + 16 * i) = z; }
;         asm volatile("s_waitcnt lgkmcnt(0)" ::: "memory"); __builtin_amdgcn_s_barrier(); asm volatile("" ::: "memory");
;         AttnRegs R;
;         if (u0 < u1) { const AttnUnit un = attn_decode(u0);
;             if (un.n > 0) { attn_issue(R, un, un.n - 1, false, PROJ, BIAS2); attn_commit(R, un.n - 1, false, lds); }
;             attn_issue(R, un, un.n, true, PROJ, BIAS2); }
.LBB0_145:
	s_add_u32 s0, s40, 0x3fc00000
	s_addc_u32 s1, s41, 0
	s_add_u32 s33, s40, 0xbc00000
	s_addc_u32 s46, s41, 0
	s_add_u32 s47, s38, 0x8000000
	s_addc_u32 s64, s39, 0
	s_add_i32 s4, s59, s10
	s_or_b32 s4, s4, s6
	s_ashr_i32 s5, s4, 31
	s_lshl_b64 s[4:5], s[4:5], 20
	v_lshrrev_b32_e32 v1, 2, v178
	s_add_u32 s4, s18, s4
	v_and_b32_e32 v33, 0xf0, v1
	s_addc_u32 s5, s19, s5
	v_or_b32_e32 v1, v33, v92
	s_add_i32 s8, s9, s8
	v_add_lshl_u32 v80, s8, v1, 8
	v_mov_b32_e32 v81, 0
	v_lshl_add_u64 v[2:3], s[4:5], 0, v[80:81]
	s_add_i32 s4, s58, s10
	v_lshrrev_b32_e32 v1, 1, v178
	s_ashr_i32 s5, s4, 31
	v_and_b32_e32 v34, 24, v1
	s_lshl_b64 s[4:5], s[4:5], 20
	v_lshlrev_b32_e32 v80, 1, v34
	v_add_u32_e32 v0, s9, v0
	s_add_u32 s4, s18, s4
	v_lshl_add_u64 v[2:3], v[2:3], 0, v[80:81]
	v_lshl_or_b32 v80, v0, 7, v91
	s_addc_u32 s5, s19, s5
	v_lshl_add_u64 v[12:13], v[80:81], 1, s[4:5]
	s_mov_b32 s65, 0x18006000
	v_add_co_u32_e32 v0, vcc, s65, v12
	s_mov_b32 s66, 0xc006000
	s_nop 0
	v_addc_co_u32_e32 v1, vcc, 0, v13, vcc
	global_load_dwordx4 v[48:51], v[2:3], off offset:192
	global_load_dwordx4 v[52:55], v[2:3], off offset:128
	global_load_dwordx4 v[56:59], v[2:3], off offset:64
	global_load_dwordx4 v[60:63], v[2:3], off
	v_add_co_u32_e32 v2, vcc, s66, v12
	s_mov_b32 s67, 0x18004000
	s_nop 0
	v_addc_co_u32_e32 v3, vcc, 0, v13, vcc
	v_add_co_u32_e32 v4, vcc, s67, v12
	s_mov_b32 s68, 0xc004000
	s_nop 0
	v_addc_co_u32_e32 v5, vcc, 0, v13, vcc
	v_add_co_u32_e32 v6, vcc, s68, v12
	s_mov_b32 s69, 0x18002000
	s_nop 0
	v_addc_co_u32_e32 v7, vcc, 0, v13, vcc
	v_add_co_u32_e32 v8, vcc, s69, v12
	s_mov_b32 s70, 0xc002000
	s_nop 0
	v_addc_co_u32_e32 v9, vcc, 0, v13, vcc
	s_lshl_b32 s4, s7, 3
	v_add_co_u32_e32 v10, vcc, s70, v12
	s_or_b32 s4, s4, s6
	s_movk_i32 s5, 0xc0
	v_addc_co_u32_e32 v11, vcc, 0, v13, vcc
	s_brev_b32 s71, 24
	s_mul_i32 s6, s4, 0xc0
	v_cmp_gt_u32_e64 s[4:5], s5, v178
	v_add_co_u32_e32 v14, vcc, s71, v12
	s_nop 0
	v_cndmask_b32_e64 v95, 0, v178, s[4:5]
	v_addc_co_u32_e32 v15, vcc, 0, v13, vcc
	s_brev_b32 s72, 48
	v_add_u32_e32 v36, s6, v95
	v_add_co_u32_e32 v12, vcc, s72, v12
	v_ashrrev_i32_e32 v37, 31, v36
	s_nop 0
	v_addc_co_u32_e32 v13, vcc, 0, v13, vcc
	v_lshl_add_u64 v[36:37], v[36:37], 2, s[56:57]
	global_load_dwordx4 v[28:31], v[0:1], off
	s_nop 0
	global_load_dwordx4 v[0:3], v[2:3], off
	s_nop 0
	global_load_dwordx4 v[16:19], v[4:5], off
	s_nop 0
	global_load_dwordx4 v[4:7], v[6:7], off
	s_nop 0
	global_load_dwordx4 v[20:23], v[8:9], off
	s_nop 0
	global_load_dwordx4 v[8:11], v[10:11], off
	s_nop 0
	global_load_dwordx4 v[24:27], v[14:15], off
	s_nop 0
	global_load_dwordx4 v[12:15], v[12:13], off
	v_lshlrev_b32_e32 v35, 2, v178
	global_load_dword v125, v[36:37], off
	s_add_i32 s6, 0, 0x20000
	v_add_u32_e32 v97, s6, v35
	v_and_b32_e32 v102, 12, v35
	v_lshrrev_b32_e32 v35, 1, v92
	v_bfe_u32 v99, v178, 4, 2
	v_and_b32_e32 v35, 2, v35
	v_or_b32_e32 v98, v33, v92
	v_lshrrev_b32_e32 v33, 2, v92
	v_bitop3_b32 v36, v35, v99, v102 bitop3:0x36
	v_or_b32_e32 v104, 4, v99
	v_lshlrev_b32_e32 v100, 3, v33
	v_lshlrev_b32_e32 v103, 4, v36
	v_bitop3_b32 v36, v35, v104, v102 bitop3:0x36
	v_or_b32_e32 v106, 8, v99
	v_or_b32_e32 v108, 12, v99
	v_lshl_or_b32 v111, v99, 3, v33
	v_lshlrev_b32_e32 v33, 1, v90
	v_lshlrev_b32_e32 v105, 4, v36
	v_bitop3_b32 v36, v35, v106, v102 bitop3:0x36
	v_bitop3_b32 v35, v35, v108, v102 bitop3:0x36
	v_and_b32_e32 v113, 12, v178
	v_and_b32_e32 v33, 2, v33
	v_lshlrev_b32_e32 v109, 4, v35
	v_bfe_u32 v112, v178, 1, 1
	v_or_b32_e32 v35, v33, v113
	v_and_b32_e32 v114, 8, v32
	v_or_b32_e32 v32, v35, v112
	v_or_b32_e32 v116, 2, v112
	v_lshlrev_b32_e32 v115, 4, v32
	v_bitop3_b32 v32, v33, v116, v113 bitop3:0x36
	v_or_b32_e32 v118, 4, v112
	v_lshlrev_b32_e32 v117, 4, v32
	v_bitop3_b32 v32, v33, v118, v113 bitop3:0x36
	v_or_b32_e32 v120, 6, v112
	v_lshlrev_b32_e32 v119, 4, v32
	v_bitop3_b32 v32, v33, v120, v113 bitop3:0x36
	v_or_b32_e32 v122, 8, v112
	v_lshlrev_b32_e32 v121, 4, v32
	v_bitop3_b32 v32, v33, v122, v113 bitop3:0x36
	v_or_b32_e32 v124, 10, v112
	v_lshlrev_b32_e32 v123, 4, v32
	v_bitop3_b32 v32, v33, v124, v113 bitop3:0x36
	v_or_b32_e32 v127, 12, v112
	v_lshlrev_b32_e32 v126, 4, v32
	v_bitop3_b32 v32, v33, v127, v113 bitop3:0x36
	v_or_b32_e32 v129, 14, v112
	v_lshlrev_b32_e32 v128, 4, v32
	v_bitop3_b32 v32, v33, v129, v113 bitop3:0x36
	v_lshlrev_b32_e32 v130, 4, v32
	v_lshlrev_b32_e32 v32, 2, v99
	v_lshlrev_b32_e32 v84, 1, v32
	v_mbcnt_lo_u32_b32 v32, -1, 0
	s_mov_b32 s9, 0
	v_or_b32_e32 v96, 0x4000, v93
	v_and_b32_e32 v101, 3, v178
	v_lshlrev_b32_e32 v107, 4, v36
	v_lshl_add_u32 v110, v99, 5, s6
	v_cmp_eq_u32_e64 s[6:7], 0, v99
	s_add_i32 s73, 0, 0x10000
	v_lshlrev_b32_e32 v82, 1, v34
	s_mov_b32 s74, 0xf149f2ca
	v_mov_b32_e32 v131, 0xf149f2ca
	v_mbcnt_hi_u32_b32 v132, -1, v32
	s_mov_b32 s94, 0
	s_add_i32 s97, s11, 1
	s_cmp_ge_i32 s97, s29
	s_cbranch_scc1 .Lp2kv_pro_skip
	s_lshr_b32 s88, s97, 8
	s_mul_hi_u32 s32, s88, 0x55555556
	s_mul_i32 s92, s32, 3
	s_sub_i32 s88, s88, s92
	s_lshl_b32 s88, s88, 6
	s_lshl_b32 s32, s32, 3
	s_add_i32 s88, s88, s32
	s_bfe_u32 s32, s97, 0x30005
	s_add_i32 s88, s88, s32
	s_lshl_b32 s88, s88, 20
	s_and_b32 s32, s97, 31
	s_lshl_b32 s32, s32, 15
	s_add_i32 s88, s88, s32
	s_add_u32 s30, s18, s88
	s_addc_u32 s31, s19, 0
	s_add_u32 s92, s30, 0xc000000
	s_addc_u32 s93, s31, 0
	s_add_u32 s98, s92, 0xc000000
	s_addc_u32 s99, s93, 0
	v_lshl_add_u32 v65, v98, 8, v82
	v_lshlrev_b32_e32 v66, 4, v178
	v_add_u32_e32 v67, 0x2000, v66
	v_add_u32_e32 v68, 0x4000, v66
	v_add_u32_e32 v69, 0x6000, v66
	global_load_dwordx4 v[246:249], v65, s[30:31]
	global_load_dwordx4 v[250:253], v65, s[30:31] offset:64
	global_load_dwordx4 v[240:243], v65, s[30:31] offset:128
	global_load_dwordx2 v[254:255], v65, s[30:31] offset:192
	global_load_dword v245, v65, s[30:31] offset:200
	global_load_dword v179, v65, s[30:31] offset:204
	global_load_dwordx4 v[220:223], v66, s[92:93]
	global_load_dwordx4 v[232:235], v66, s[98:99]
	global_load_dwordx4 v[216:219], v67, s[92:93]
	global_load_dwordx4 v[228:231], v67, s[98:99]
	global_load_dwordx4 v[212:215], v68, s[92:93]
	global_load_dwordx4 v[224:227], v68, s[98:99]
	global_load_dwordx4 v[208:211], v69, s[92:93]
	global_load_dwordx4 v[236:239], v69, s[98:99]

; __global__ void __launch_bounds__(NTHREADS, 2) fwd_megakernel(Args args) {
;     ...
;         for (int uid = u0; uid < u1; ++uid) {
;             const AttnUnit u = attn_decode(uid);
;             attn_commit(R, u.n, true, lds);
;             bf16x8 qf[4];
; #pragma unroll
;             for (int s4 = 0; s4 < 4; ++s4) qf[s4] = R.qf[s4];
;             asm volatile("s_waitcnt lgkmcnt(0)" ::: "memory"); __builtin_amdgcn_s_barrier(); asm volatile("" ::: "memory");
;             if (uid + 1 < u1) { const AttnUnit un = attn_decode(uid + 1); attn_issue(R, un, un.n, true, PROJ, BIAS2); }
;             bf16* og = u.g == 0 ? OG0 : (u.g == 1 ? OG1 : OG2);
;             attn_compute(lds, qf, u, og, LSE + (size_t)u.g * MTOK * 8);
;             asm volatile("s_waitcnt lgkmcnt(0)" ::: "memory"); __builtin_amdgcn_s_barrier(); asm volatile("" ::: "memory");
.LBB0_146:
	s_or_b64 exec, exec, s[60:61]
	s_waitcnt lgkmcnt(0)
	s_barrier
	s_add_i32 s97, s75, 1
	s_cmp_ge_i32 s97, s29
	s_cbranch_scc1 .Lp2_wait_tail
	s_cmp_eq_u32 s94, 0
	s_cbranch_scc1 .Lp2_wait_even
	s_waitcnt vmcnt(23)
	s_branch .Lp2_wait_done
.Lp2_wait_even:
	s_waitcnt vmcnt(21)
	s_branch .Lp2_wait_done

; #define LAS __attribute__((address_space(3)))
; __device__ __forceinline__ void attn_commit(const AttnRegs& R, int blk, bool with_tab, LAS unsigned char* lds) {
;     const int tid = threadIdx.x; const int ch = tid & 15, r0 = tid >> 4;
;     LAS unsigned char* Ks = lds; LAS unsigned char* Vs = lds + 65536; LAS float* tab = (LAS float*)(lds + LDS_TAB);
; #pragma unroll
;     for (int j = 0; j < 4; ++j) { const unsigned row = (blk & 1) * 128 + r0 + 32 * j; *(LAS v4u*)(Ks + off_b(row, ch)) = R.kr[j]; *(LAS v4u*)(Vs + off_b(row, ch)) = R.vr[j]; }
;     if (with_tab && tid < 192) tab[tid] = R.tabv;
; }
; __global__ void __launch_bounds__(NTHREADS, 2) fwd_megakernel(Args args) {
;     ...
;         for (int uid = u0; uid < u1; ++uid) {
;             const AttnUnit u = attn_decode(uid);
;             attn_commit(R, u.n, true, lds);
;             bf16x8 qf[4];
; #pragma unroll
;             for (int s4 = 0; s4 < 4; ++s4) qf[s4] = R.qf[s4];
.Lp2_wait_done:
	s_xor_b32 s94, s94, 1
	s_cmp_eq_u32 s94, 0
	s_cbranch_scc1 .Lp2_qcopy_a
	v_mov_b64_e32 v[60:61], v[246:247]
	v_mov_b64_e32 v[62:63], v[248:249]
	v_mov_b64_e32 v[56:57], v[250:251]
	v_mov_b64_e32 v[58:59], v[252:253]
	v_mov_b64_e32 v[52:53], v[240:241]
	v_mov_b64_e32 v[54:55], v[242:243]
	v_mov_b64_e32 v[48:49], v[254:255]
	v_mov_b32_e32 v50, v245
	v_mov_b32_e32 v51, v179
	s_branch .Lp2_qcopy_done
.Lp2_qcopy_a:
	v_mov_b64_e32 v[62:63], v[34:35]
	v_mov_b64_e32 v[58:59], v[38:39]
	v_mov_b64_e32 v[54:55], v[42:43]
	v_mov_b64_e32 v[50:51], v[46:47]
	v_mov_b64_e32 v[60:61], v[32:33]
	v_mov_b64_e32 v[56:57], v[36:37]
	v_mov_b64_e32 v[52:53], v[40:41]
	v_mov_b64_e32 v[48:49], v[44:45]
.Lp2_qcopy_done:
	s_and_b64 vcc, exec, s[58:59]
	s_mov_b32 s11, s75
	s_cbranch_vccnz .LBB0_153
.LBB0_147:
	s_cmp_eq_u32 s94, 0
	s_cbranch_scc1 .Lp2_commit_r1
	s_ashr_i32 s8, s11, 8
	s_mul_hi_i32 s10, s8, 0x55555556
	s_lshr_b32 s30, s10, 31
	s_add_i32 s62, s10, s30
	s_mul_i32 s10, s62, 3
	s_sub_i32 s10, s8, s10
	s_lshl_b32 s8, s10, 1
	s_lshr_b32 s30, 32, s8
	s_and_b32 s63, s11, 31
	s_add_i32 s30, s30, -1
	s_and_b32 s84, s30, s63
	s_lshl_b32 s81, s84, 7
	s_and_b32 s30, s81, 0x80
	v_or_b32_e32 v70, s30, v90
	v_lshlrev_b32_e32 v71, 8, v70
	v_or_b32_e32 v72, v71, v93
	v_add_u32_e32 v73, 0, v72
	v_add_u32_e32 v72, s73, v72
	ds_write_b128 v72, v[232:235]
	v_add_u32_e32 v72, 32, v70
	ds_write_b128 v73, v[220:223]
	v_lshlrev_b32_e32 v73, 8, v72
	v_lshlrev_b32_e32 v72, 2, v72
	v_and_b32_e32 v72, 12, v72
	v_bitop3_b32 v72, v72, v92, v94 bitop3:0x36
	v_lshl_or_b32 v72, v72, 4, v73
	v_add_u32_e32 v73, 0, v72
	v_add_u32_e32 v72, s73, v72
	ds_write_b128 v72, v[228:231]
	v_or_b32_e32 v72, v71, v96
	v_add3_u32 v71, v71, v93, 0
	ds_write_b128 v73, v[216:219]
	ds_write_b128 v71, v[212:215] offset:16384
	v_add_u32_e32 v71, s73, v72
	v_add_u32_e32 v70, 0x60, v70
	ds_write_b128 v71, v[224:227]
	v_lshlrev_b32_e32 v71, 8, v70
	v_lshlrev_b32_e32 v70, 2, v70
	v_and_b32_e32 v70, 12, v70
	v_bitop3_b32 v70, v70, v92, v94 bitop3:0x36
	v_lshl_or_b32 v70, v70, 4, v71
	v_add_u32_e32 v71, 0, v70
	v_add_u32_e32 v70, s73, v70
	ds_write_b128 v71, v[208:211]
	ds_write_b128 v70, v[236:239]
	s_branch .Lp2_commit_done
.Lp2_commit_r1:
	s_ashr_i32 s8, s11, 8
	s_mul_hi_i32 s10, s8, 0x55555556
	s_lshr_b32 s30, s10, 31
	s_add_i32 s62, s10, s30
	s_mul_i32 s10, s62, 3
	s_sub_i32 s10, s8, s10
	s_lshl_b32 s8, s10, 1
	s_lshr_b32 s30, 32, s8
	s_and_b32 s63, s11, 31
	s_add_i32 s30, s30, -1
	s_and_b32 s84, s30, s63
	s_lshl_b32 s81, s84, 7
	s_and_b32 s30, s81, 0x80
	v_or_b32_e32 v70, s30, v90
	v_lshlrev_b32_e32 v71, 8, v70
	v_or_b32_e32 v72, v71, v93
	v_add_u32_e32 v73, 0, v72
	v_add_u32_e32 v72, s73, v72
	ds_write_b128 v72, v[24:27]
	v_add_u32_e32 v72, 32, v70
	ds_write_b128 v73, v[12:15]
	v_lshlrev_b32_e32 v73, 8, v72
	v_lshlrev_b32_e32 v72, 2, v72
	v_and_b32_e32 v72, 12, v72
	v_bitop3_b32 v72, v72, v92, v94 bitop3:0x36
	v_lshl_or_b32 v72, v72, 4, v73
	v_add_u32_e32 v73, 0, v72
	v_add_u32_e32 v72, s73, v72
	ds_write_b128 v72, v[20:23]
	v_or_b32_e32 v72, v71, v96
	v_add3_u32 v71, v71, v93, 0
	ds_write_b128 v73, v[8:11]
	ds_write_b128 v71, v[4:7] offset:16384
	v_add_u32_e32 v71, s73, v72
	v_add_u32_e32 v70, 0x60, v70
	ds_write_b128 v71, v[16:19]
	v_lshlrev_b32_e32 v71, 8, v70
	v_lshlrev_b32_e32 v70, 2, v70
	v_and_b32_e32 v70, 12, v70
	v_bitop3_b32 v70, v70, v92, v94 bitop3:0x36
	v_lshl_or_b32 v70, v70, 4, v71
	v_add_u32_e32 v71, 0, v70
	v_add_u32_e32 v70, s73, v70
	ds_write_b128 v71, v[0:3]
	ds_write_b128 v70, v[28:31]

; __device__ __forceinline__ void attn_issue(AttnRegs& R, const AttnUnit& u, int blk, bool with_q, const bf16* qkv, const float* bias2) {
;     const int tid = threadIdx.x, lane = tid & 63, w = tid >> 6;
;     const int L = 4096 >> (2 * u.g), gh = u.g * 8 + u.h;
;     const int ch = tid & 15, r0 = tid >> 4;
;     if (with_q) R.tabv = bias2[gh * 192 + (tid < 192 ? tid : 0)];
;     const size_t rb = (size_t)(u.r * L + blk * 128 + r0) * 128 + ch * 8;
;     const bf16* kp = attn_plane(qkv, 1, u) + rb; const bf16* vp = attn_plane(qkv, 2, u) + rb;
; #pragma unroll
;     for (int j = 0; j < 4; ++j) { R.kr[j] = *(const v4u*)(kp + (size_t)j * 32 * 128); R.vr[j] = *(const v4u*)(vp + (size_t)j * 32 * 128); }
;     if (with_q) {
;         const int qi = 16 * w + (lane & 15), kg = lane >> 4;
;         const bf16* qp = attn_plane(qkv, 0, u) + (size_t)(u.r * L + u.n * 128 + qi) * 128 + 8 * kg;
; #pragma unroll
;         for (int s = 0; s < 4; ++s) R.qf[s] = *(const bf16x8*)(qp + 32 * s);
;     }
; __global__ void __launch_bounds__(NTHREADS, 2) fwd_megakernel(Args args) {
;     ...
;             asm volatile("s_waitcnt lgkmcnt(0)" ::: "memory"); __builtin_amdgcn_s_barrier(); asm volatile("" ::: "memory");
;             if (uid + 1 < u1) { const AttnUnit un = attn_decode(uid + 1); attn_issue(R, un, un.n, true, PROJ, BIAS2); }
.LBB0_149:
	s_or_b64 exec, exec, s[58:59]
	s_add_i32 s75, s11, 1
	s_waitcnt lgkmcnt(0)
	s_barrier
	s_cmp_ge_i32 s75, s29
	s_cselect_b64 s[58:59], -1, 0
	s_and_b64 vcc, exec, s[58:59]
	s_cbranch_vccnz .LBB0_151
	s_and_b32 s32, s75, 31
	s_cmp_lg_u32 s32, 0
	s_cbranch_scc1 .Lp2_nobias
	s_lshr_b32 s88, s75, 8
	s_mul_hi_u32 s32, s88, 0x55555556
	s_mul_i32 s97, s32, 3
	s_sub_i32 s88, s88, s97
	s_bfe_u32 s97, s75, 0x30005
	s_lshl_b32 s30, s88, 3
	s_or_b32 s30, s30, s97
	s_mulk_i32 s30, 0xc0
	v_add_lshl_u32 v64, s30, v95, 2
	global_load_dword v125, v64, s[56:57]
.Lp2_nobias:
	s_add_i32 s97, s75, 1
	s_cmp_ge_i32 s97, s29
	s_cbranch_scc1 .Lp2_kv_done
	s_lshr_b32 s88, s97, 8
	s_mul_hi_u32 s32, s88, 0x55555556
	s_mul_i32 s92, s32, 3
	s_sub_i32 s88, s88, s92
	s_lshl_b32 s88, s88, 6
	s_lshl_b32 s32, s32, 3
	s_add_i32 s88, s88, s32
	s_bfe_u32 s32, s97, 0x30005
	s_add_i32 s88, s88, s32
	s_lshl_b32 s88, s88, 20
	s_and_b32 s32, s97, 31
	s_lshl_b32 s32, s32, 15
	s_add_i32 s88, s88, s32
	s_add_u32 s30, s18, s88
	s_addc_u32 s31, s19, 0
	s_add_u32 s92, s30, 0xc000000
	s_addc_u32 s93, s31, 0
	s_add_u32 s98, s92, 0xc000000
	s_addc_u32 s99, s93, 0
	v_lshl_add_u32 v65, v98, 8, v82
	v_lshlrev_b32_e32 v66, 4, v178
	v_add_u32_e32 v67, 0x2000, v66
	v_add_u32_e32 v68, 0x4000, v66
	v_add_u32_e32 v69, 0x6000, v66
	s_cmp_eq_u32 s94, 0
	s_cbranch_scc1 .Lp2_kv_r1
	global_load_dwordx4 v[246:249], v65, s[30:31]
	global_load_dwordx4 v[250:253], v65, s[30:31] offset:64
	global_load_dwordx4 v[240:243], v65, s[30:31] offset:128
	global_load_dwordx2 v[254:255], v65, s[30:31] offset:192
	global_load_dword v245, v65, s[30:31] offset:200
	global_load_dword v179, v65, s[30:31] offset:204
	global_load_dwordx4 v[220:223], v66, s[92:93]
	global_load_dwordx4 v[232:235], v66, s[98:99]
	global_load_dwordx4 v[216:219], v67, s[92:93]
	global_load_dwordx4 v[228:231], v67, s[98:99]
	global_load_dwordx4 v[212:215], v68, s[92:93]
	global_load_dwordx4 v[224:227], v68, s[98:99]
	global_load_dwordx4 v[208:211], v69, s[92:93]
	global_load_dwordx4 v[236:239], v69, s[98:99]
	s_branch .Lp2_kv_done
.Lp2_kv_r1:
	global_load_dwordx4 v[32:35], v65, s[30:31]
	global_load_dwordx4 v[36:39], v65, s[30:31] offset:64
	global_load_dwordx4 v[40:43], v65, s[30:31] offset:128
	global_load_dwordx4 v[44:47], v65, s[30:31] offset:192
	global_load_dwordx4 v[12:15], v66, s[92:93]
	global_load_dwordx4 v[24:27], v66, s[98:99]
	global_load_dwordx4 v[8:11], v67, s[92:93]
	global_load_dwordx4 v[20:23], v67, s[98:99]
	global_load_dwordx4 v[4:7], v68, s[92:93]
	global_load_dwordx4 v[16:19], v68, s[98:99]
	global_load_dwordx4 v[0:3], v69, s[92:93]
	global_load_dwordx4 v[28:31], v69, s[98:99]

; __global__ void __launch_bounds__(NTHREADS, 2) fwd_megakernel(Args args) {
	.amdhsa_kernel _Z14fwd_megakernel4Args
		.amdhsa_group_segment_fixed_size 0
		.amdhsa_private_segment_fixed_size 0
		.amdhsa_kernarg_size 376
		.amdhsa_user_sgpr_count 2
		.amdhsa_user_sgpr_dispatch_ptr 0
		.amdhsa_user_sgpr_queue_ptr 0
		.amdhsa_user_sgpr_kernarg_segment_ptr 1
		.amdhsa_user_sgpr_dispatch_id 0
		.amdhsa_user_sgpr_kernarg_preload_length 0
		.amdhsa_user_sgpr_kernarg_preload_offset 0
		.amdhsa_user_sgpr_private_segment_size 0
		.amdhsa_uses_dynamic_stack 0
		.amdhsa_enable_private_segment 0
		.amdhsa_system_sgpr_workgroup_id_x 1
		.amdhsa_system_sgpr_workgroup_id_y 0
		.amdhsa_system_sgpr_workgroup_id_z 0
		.amdhsa_system_sgpr_workgroup_info 0
		.amdhsa_system_vgpr_workitem_id 2
		.amdhsa_next_free_vgpr 256
		.amdhsa_next_free_sgpr 100
		.amdhsa_accum_offset 256
		.amdhsa_reserve_vcc 1
		.amdhsa_float_round_mode_32 0
		.amdhsa_float_round_mode_16_64 0
		.amdhsa_float_denorm_mode_32 3
		.amdhsa_float_denorm_mode_16_64 3
		.amdhsa_dx10_clamp 1
		.amdhsa_ieee_mode 1
		.amdhsa_fp16_overflow 0
		.amdhsa_tg_split 0
		.amdhsa_exception_fp_ieee_invalid_op 0
		.amdhsa_exception_fp_denorm_src 0
		.amdhsa_exception_fp_ieee_div_zero 0
		.amdhsa_exception_fp_ieee_overflow 0
		.amdhsa_exception_fp_ieee_underflow 0
		.amdhsa_exception_fp_ieee_inexact 0
		.amdhsa_exception_int_div_zero 0
	.end_amdhsa_kernel

; __global__ void __launch_bounds__(NTHREADS, 2) fwd_megakernel(Args args) {
amdhsa.kernels:
  - .agpr_count:     0
    .args:
      - .offset:         0
        .size:           120
        .value_kind:     by_value
      - .offset:         120
        .size:           4
        .value_kind:     hidden_block_count_x
      - .offset:         124
        .size:           4
        .value_kind:     hidden_block_count_y
      - .offset:         128
        .size:           4
        .value_kind:     hidden_block_count_z
      - .offset:         132
        .size:           2
        .value_kind:     hidden_group_size_x
      - .offset:         134
        .size:           2
        .value_kind:     hidden_group_size_y
      - .offset:         136
        .size:           2
        .value_kind:     hidden_group_size_z
      - .offset:         138
        .size:           2
        .value_kind:     hidden_remainder_x
      - .offset:         140
        .size:           2
        .value_kind:     hidden_remainder_y
      - .offset:         142
        .size:           2
        .value_kind:     hidden_remainder_z
      - .offset:         160
        .size:           8
        .value_kind:     hidden_global_offset_x
      - .offset:         168
        .size:           8
        .value_kind:     hidden_global_offset_y
      - .offset:         176
        .size:           8
        .value_kind:     hidden_global_offset_z
      - .offset:         184
        .size:           2
        .value_kind:     hidden_grid_dims
      - .offset:         208
        .size:           8
        .value_kind:     hidden_multigrid_sync_arg
      - .offset:         240
        .size:           4
        .value_kind:     hidden_dynamic_lds_size
    .group_segment_fixed_size: 0
    .kernarg_segment_align: 8
    .kernarg_segment_size: 376
    .language:       OpenCL C
    .language_version:
      - 2
      - 0
    .max_flat_workgroup_size: 512
    .name:           _Z14fwd_megakernel4Args
    .private_segment_fixed_size: 0
    .sgpr_count:     106
    .sgpr_spill_count: 11
    .symbol:         _Z14fwd_megakernel4Args.kd
    .uniform_work_group_size: 1
    .uses_dynamic_stack: false
    .vgpr_count:     256
    .vgpr_spill_count: 0
    .wavefront_size: 64
